# MLA key-tile loop hand-scheduled: pipelined K/V LDS reads, max3 tree, permlane swap, exp overlapped with PV MFMAs, conditional O rescale
# speedup vs baseline: 1.0226x; 1.0226x over previous
.LBB0_917:
	s_bitcmp1_b32 s8, 0
	s_cselect_b32 s6, 0x5800, 0
	v_add_u32_e32 v32, s6, v176
	v_add_u32_e32 v173, v32, v128
	ds_read_b128 v[218:221], v173
	ds_read_b128 v[222:225], v173 offset:6656
	ds_read_b128 v[226:229], v173 offset:32
	ds_read_b128 v[230:233], v173 offset:6688
	ds_read_b128 v[234:237], v173 offset:64
	ds_read_b128 v[238:241], v173 offset:6720
	ds_read_b128 v[242:245], v173 offset:96
	ds_read_b128 v[246:249], v173 offset:6752
	v_mov_b32_e32 v184, v177
	v_mov_b32_e32 v185, v108
	v_add_u32_e32 v174, s6, v175
	v_cmp_lt_i32_e64 s[0:1], v153, v147
	v_add_u32_e32 v174, v174, v122
	v_add_u32_e32 v172, 0x4000, v174
	v_cndmask_b32_e64 v171, v146, v153, s[0:1]
	v_add_u32_e32 v174, 0x3000, v174
	v_lshlrev_b32_e32 v171, 2, v171
	s_waitcnt lgkmcnt(7)
	v_mfma_f32_32x32x16_bf16 v[48:63], v[218:221], v[68:71], 0
	s_waitcnt lgkmcnt(6)
	v_mfma_f32_32x32x16_bf16 v[32:47], v[222:225], v[68:71], 0
	ds_read_b128 v[218:221], v173 offset:128
	ds_read_b128 v[222:225], v173 offset:6784
	s_waitcnt lgkmcnt(7)
	v_mfma_f32_32x32x16_bf16 v[48:63], v[226:229], v[72:75], v[48:63]
	s_waitcnt lgkmcnt(6)
	v_mfma_f32_32x32x16_bf16 v[32:47], v[230:233], v[72:75], v[32:47]
	ds_read_b128 v[226:229], v173 offset:160
	ds_read_b128 v[230:233], v173 offset:6816
	s_waitcnt lgkmcnt(7)
	v_mfma_f32_32x32x16_bf16 v[48:63], v[234:237], v[84:87], v[48:63]
	s_waitcnt lgkmcnt(6)
	v_mfma_f32_32x32x16_bf16 v[32:47], v[238:241], v[84:87], v[32:47]
	s_waitcnt lgkmcnt(5)
	v_mfma_f32_32x32x16_bf16 v[48:63], v[242:245], v[80:83], v[48:63]
	s_waitcnt lgkmcnt(4)
	v_mfma_f32_32x32x16_bf16 v[32:47], v[246:249], v[80:83], v[32:47]
	ds_read2_b64 v[234:237], v174 offset0:128 offset1:130
	ds_read2_b64 v[238:241], v172 offset0:160 offset1:162
	ds_read2_b64 v[242:245], v174 offset0:132 offset1:134
	ds_read2_b64 v[246:249], v172 offset0:164 offset1:166
	s_waitcnt lgkmcnt(7)
	v_mfma_f32_32x32x16_bf16 v[48:63], v[218:221], v[92:95], v[48:63]
	s_waitcnt lgkmcnt(6)
	v_mfma_f32_32x32x16_bf16 v[32:47], v[222:225], v[92:95], v[32:47]
	s_waitcnt lgkmcnt(5)
	v_mfma_f32_32x32x16_bf16 v[48:63], v[226:229], v[88:91], v[48:63]
	s_waitcnt lgkmcnt(4)
	v_mfma_f32_32x32x16_bf16 v[32:47], v[230:233], v[88:91], v[32:47]
	ds_read2_b64 v[218:221], v174 offset0:136 offset1:138
	ds_read2_b64 v[222:225], v172 offset0:168 offset1:170
	ds_read2_b64 v[226:229], v174 offset0:140 offset1:142
	ds_read2_b64 v[230:233], v172 offset0:172 offset1:174
	s_add_i32 s8, s8, 1
	s_bitcmp1_b32 s8, 0
	s_cselect_b32 s0, 0x5800, 0
	v_add3_u32 v179, s0, v123, v125
	s_waitcnt vmcnt(4)
	ds_write_b128 v179, v[64:67]
	v_add3_u32 v179, s0, v129, v166
	s_waitcnt vmcnt(3)
	ds_write_b128 v179, v[76:79]
	v_add3_u32 v179, s0, v167, v168
	s_waitcnt vmcnt(2)
	ds_write_b128 v179, v[96:99]
	v_add_u32_e32 v179, s0, v169
	v_add3_u32 v179, v179, v124, s63
	s_waitcnt vmcnt(1)
	ds_write2_b64 v179, v[100:101], v[102:103] offset1:1
	v_add_u32_e32 v179, s0, v170
	v_add3_u32 v179, v179, v124, s63
	s_waitcnt vmcnt(0)
	ds_write2_b64 v179, v[104:105], v[106:107] offset1:1
	v_lshl_add_u64 v[180:181], v[140:141], 0, s[56:57]
	v_lshl_add_u64 v[182:183], v[134:135], 0, s[56:57]
	v_cndmask_b32_e32 v181, v183, v181, vcc
	v_cndmask_b32_e32 v180, v182, v180, vcc
	global_load_dwordx4 v[64:67], v[180:181], off
	v_lshl_add_u64 v[180:181], v[142:143], 0, s[56:57]
	v_lshl_add_u64 v[182:183], v[136:137], 0, s[56:57]
	v_cndmask_b32_e64 v181, v183, v181, s[2:3]
	v_cndmask_b32_e64 v180, v182, v180, s[2:3]
	global_load_dwordx4 v[76:79], v[180:181], off
	v_lshl_add_u64 v[180:181], v[144:145], 0, s[56:57]
	v_lshl_add_u64 v[182:183], v[138:139], 0, s[56:57]
	v_cndmask_b32_e64 v181, v183, v181, s[4:5]
	v_cndmask_b32_e64 v180, v182, v180, s[4:5]
	global_load_dwordx4 v[96:99], v[180:181], off
	v_lshl_add_u64 v[180:181], v[130:131], 0, s[56:57]
	global_load_dwordx4 v[100:103], v[180:181], off offset:256
	v_lshl_add_u64 v[180:181], v[132:133], 0, s[56:57]
	global_load_dwordx4 v[104:107], v[180:181], off offset:256
	v_lshl_add_u64 v[130:131], v[130:131], 0, s[12:13]
	v_lshl_add_u64 v[132:133], v[132:133], 0, s[12:13]
	v_lshl_add_u64 v[134:135], v[134:135], 0, s[34:35]
	v_lshl_add_u64 v[136:137], v[136:137], 0, s[34:35]
	v_lshl_add_u64 v[138:139], v[138:139], 0, s[34:35]
	v_lshl_add_u64 v[140:141], v[140:141], 0, s[76:77]
	v_lshl_add_u64 v[142:143], v[142:143], 0, s[76:77]
	v_lshl_add_u64 v[144:145], v[144:145], 0, s[76:77]
	v_max3_f32 v252, v185, v48, v49
	v_max3_f32 v253, v32, v33, v34
	v_max3_f32 v252, v252, v50, v51
	v_max3_f32 v253, v253, v35, v36
	v_max3_f32 v252, v252, v52, v53
	v_max3_f32 v253, v253, v37, v38
	v_max3_f32 v252, v252, v54, v55
	v_max3_f32 v253, v253, v39, v40
	v_max3_f32 v252, v252, v56, v57
	v_max3_f32 v253, v253, v41, v42
	v_max3_f32 v252, v252, v58, v59
	v_max3_f32 v253, v253, v43, v44
	v_max3_f32 v252, v252, v60, v61
	v_max3_f32 v253, v253, v45, v46
	v_max3_f32 v252, v252, v62, v63
	v_max3_f32 v108, v252, v253, v47
	v_mov_b32_e32 v252, v108
	s_nop 1
	v_permlane32_swap_b32_e32 v252, v108
	v_max_f32_e32 v108, v252, v108
	v_sub_f32_e32 v178, v185, v108
	v_exp_f32_e32 v178, v178
	v_sub_f32_e32 v48, v48, v108
	v_sub_f32_e32 v49, v49, v108
	v_sub_f32_e32 v50, v50, v108
	v_sub_f32_e32 v51, v51, v108
	v_sub_f32_e32 v52, v52, v108
	v_sub_f32_e32 v53, v53, v108
	v_sub_f32_e32 v54, v54, v108
	v_sub_f32_e32 v55, v55, v108
	v_cmp_neq_f32_e64 s[98:99], 1.0, v178
	v_exp_f32_e32 v48, v48
	v_exp_f32_e32 v49, v49
	v_exp_f32_e32 v50, v50
	v_exp_f32_e32 v51, v51
	v_exp_f32_e32 v52, v52
	v_exp_f32_e32 v53, v53
	v_exp_f32_e32 v54, v54
	v_exp_f32_e32 v55, v55
	s_cmp_eq_u64 s[98:99], 0
	s_cbranch_scc1 .Lmla_noscale
	v_pk_mul_f32 v[30:31], v[30:31], v[178:179] op_sel_hi:[1,0]
	v_pk_mul_f32 v[28:29], v[28:29], v[178:179] op_sel_hi:[1,0]
	v_pk_mul_f32 v[26:27], v[26:27], v[178:179] op_sel_hi:[1,0]
	v_pk_mul_f32 v[24:25], v[24:25], v[178:179] op_sel_hi:[1,0]
	v_pk_mul_f32 v[22:23], v[22:23], v[178:179] op_sel_hi:[1,0]
	v_pk_mul_f32 v[20:21], v[20:21], v[178:179] op_sel_hi:[1,0]
	v_pk_mul_f32 v[18:19], v[18:19], v[178:179] op_sel_hi:[1,0]
	v_pk_mul_f32 v[16:17], v[16:17], v[178:179] op_sel_hi:[1,0]
	v_pk_mul_f32 v[14:15], v[14:15], v[178:179] op_sel_hi:[1,0]
	v_pk_mul_f32 v[12:13], v[12:13], v[178:179] op_sel_hi:[1,0]
	v_pk_mul_f32 v[10:11], v[10:11], v[178:179] op_sel_hi:[1,0]
	v_pk_mul_f32 v[8:9], v[8:9], v[178:179] op_sel_hi:[1,0]
	v_pk_mul_f32 v[6:7], v[6:7], v[178:179] op_sel_hi:[1,0]
	v_pk_mul_f32 v[4:5], v[4:5], v[178:179] op_sel_hi:[1,0]
	v_pk_mul_f32 v[2:3], v[2:3], v[178:179] op_sel_hi:[1,0]
	v_pk_mul_f32 v[0:1], v[0:1], v[178:179] op_sel_hi:[1,0]
.Lmla_noscale:
	v_add_f32_e32 v254, v48, v49
	v_add_f32_e32 v255, v50, v51
	v_add_f32_e32 v254, v254, v52
	v_add_f32_e32 v255, v255, v53
	v_add_f32_e32 v254, v254, v54
	v_add_f32_e32 v255, v255, v55
	v_cvt_pk_bf16_f32 v48, v48, v49
	v_cvt_pk_bf16_f32 v49, v50, v51
	v_cvt_pk_bf16_f32 v50, v52, v53
	v_cvt_pk_bf16_f32 v51, v54, v55
	v_sub_f32_e32 v56, v56, v108
	v_sub_f32_e32 v57, v57, v108
	s_waitcnt lgkmcnt(0)
	v_mfma_f32_32x32x16_bf16 v[16:31], v[234:237], v[48:51], v[16:31]
	v_sub_f32_e32 v58, v58, v108
	v_sub_f32_e32 v59, v59, v108
	v_sub_f32_e32 v60, v60, v108
	v_sub_f32_e32 v61, v61, v108
	v_sub_f32_e32 v62, v62, v108
	v_sub_f32_e32 v63, v63, v108
	v_mfma_f32_32x32x16_bf16 v[0:15], v[238:241], v[48:51], v[0:15]
	v_exp_f32_e32 v56, v56
	v_exp_f32_e32 v57, v57
	v_exp_f32_e32 v58, v58
	v_exp_f32_e32 v59, v59
	v_exp_f32_e32 v60, v60
	v_exp_f32_e32 v61, v61
	v_exp_f32_e32 v62, v62
	v_exp_f32_e32 v63, v63
	v_add_f32_e32 v254, v254, v56
	v_add_f32_e32 v255, v255, v57
	v_add_f32_e32 v254, v254, v58
	v_add_f32_e32 v255, v255, v59
	v_add_f32_e32 v254, v254, v60
	v_add_f32_e32 v255, v255, v61
	v_add_f32_e32 v254, v254, v62
	v_add_f32_e32 v255, v255, v63
	v_cvt_pk_bf16_f32 v56, v56, v57
	v_cvt_pk_bf16_f32 v57, v58, v59
	v_cvt_pk_bf16_f32 v58, v60, v61
	v_cvt_pk_bf16_f32 v59, v62, v63
	v_sub_f32_e32 v32, v32, v108
	v_sub_f32_e32 v33, v33, v108
	v_mfma_f32_32x32x16_bf16 v[16:31], v[242:245], v[56:59], v[16:31]
	v_sub_f32_e32 v34, v34, v108
	v_sub_f32_e32 v35, v35, v108
	v_sub_f32_e32 v36, v36, v108
	v_sub_f32_e32 v37, v37, v108
	v_sub_f32_e32 v38, v38, v108
	v_sub_f32_e32 v39, v39, v108
	v_mfma_f32_32x32x16_bf16 v[0:15], v[246:249], v[56:59], v[0:15]
	v_exp_f32_e32 v32, v32
	v_exp_f32_e32 v33, v33
	v_exp_f32_e32 v34, v34
	v_exp_f32_e32 v35, v35
	v_exp_f32_e32 v36, v36
	v_exp_f32_e32 v37, v37
	v_exp_f32_e32 v38, v38
	v_exp_f32_e32 v39, v39
	v_add_f32_e32 v254, v254, v32
	v_add_f32_e32 v255, v255, v33
	v_add_f32_e32 v254, v254, v34
	v_add_f32_e32 v255, v255, v35
	v_add_f32_e32 v254, v254, v36
	v_add_f32_e32 v255, v255, v37
	v_add_f32_e32 v254, v254, v38
	v_add_f32_e32 v255, v255, v39
	v_cvt_pk_bf16_f32 v32, v32, v33
	v_cvt_pk_bf16_f32 v33, v34, v35
	v_cvt_pk_bf16_f32 v34, v36, v37
	v_cvt_pk_bf16_f32 v35, v38, v39
	v_sub_f32_e32 v40, v40, v108
	v_sub_f32_e32 v41, v41, v108
	v_mfma_f32_32x32x16_bf16 v[16:31], v[218:221], v[32:35], v[16:31]
	v_sub_f32_e32 v42, v42, v108
	v_sub_f32_e32 v43, v43, v108
	v_sub_f32_e32 v44, v44, v108
	v_sub_f32_e32 v45, v45, v108
	v_sub_f32_e32 v46, v46, v108
	v_sub_f32_e32 v47, v47, v108
	v_mfma_f32_32x32x16_bf16 v[0:15], v[222:225], v[32:35], v[0:15]
	v_exp_f32_e32 v40, v40
	v_exp_f32_e32 v41, v41
	v_exp_f32_e32 v42, v42
	v_exp_f32_e32 v43, v43
	v_exp_f32_e32 v44, v44
	v_exp_f32_e32 v45, v45
	v_exp_f32_e32 v46, v46
	v_exp_f32_e32 v47, v47
	v_add_f32_e32 v254, v254, v40
	v_add_f32_e32 v255, v255, v41
	v_add_f32_e32 v254, v254, v42
	v_add_f32_e32 v255, v255, v43
	v_add_f32_e32 v254, v254, v44
	v_add_f32_e32 v255, v255, v45
	v_add_f32_e32 v254, v254, v46
	v_add_f32_e32 v255, v255, v47
	v_cvt_pk_bf16_f32 v40, v40, v41
	v_cvt_pk_bf16_f32 v41, v42, v43
	v_cvt_pk_bf16_f32 v42, v44, v45
	v_cvt_pk_bf16_f32 v43, v46, v47
	v_add_f32_e32 v254, v254, v255
	v_mov_b32_e32 v252, v254
	v_mfma_f32_32x32x16_bf16 v[16:31], v[226:229], v[40:43], v[16:31]
	v_mfma_f32_32x32x16_bf16 v[0:15], v[230:233], v[40:43], v[0:15]
	v_permlane32_swap_b32_e32 v252, v254
	v_add_f32_e32 v177, v252, v254
	v_fmac_f32_e32 v177, v184, v178
	s_cmp_eq_u32 s7, s8
	s_waitcnt lgkmcnt(0)
	s_barrier
	s_cbranch_scc0 .LBB0_917
	v_add3_u32 v128, s0, v176, v128
	ds_read_b128 v[32:35], v128
	ds_read_b128 v[130:133], v128 offset:32
	v_readlane_b32 s2, v215, 56
	v_lshlrev_b64 v[126:127], 10, v[126:127]
	v_readlane_b32 s3, v215, 57
	s_lshl_b32 s86, s86, 1
	s_waitcnt lgkmcnt(1)
	v_mfma_f32_32x32x16_bf16 v[48:63], v[32:35], v[68:71], 0
	ds_read_b128 v[32:35], v128 offset:6656
	v_lshl_add_u64 v[126:127], s[2:3], 0, v[126:127]
	v_lshl_add_u64 v[126:127], v[126:127], 0, s[86:87]
	s_waitcnt lgkmcnt(1)
	v_mfma_f32_32x32x16_bf16 v[48:63], v[130:133], v[72:75], v[48:63]
	ds_read_b128 v[130:133], v128 offset:6688
	s_waitcnt lgkmcnt(1)
	v_mfma_f32_32x32x16_bf16 v[32:47], v[32:35], v[68:71], 0
	s_waitcnt lgkmcnt(0)
	v_mfma_f32_32x32x16_bf16 v[32:47], v[130:133], v[72:75], v[32:47]
	ds_read_b128 v[130:133], v128 offset:64
	s_waitcnt lgkmcnt(0)
	v_mfma_f32_32x32x16_bf16 v[48:63], v[130:133], v[84:87], v[48:63]
	ds_read_b128 v[130:133], v128 offset:6720
	s_waitcnt lgkmcnt(0)
	v_mfma_f32_32x32x16_bf16 v[32:47], v[130:133], v[84:87], v[32:47]
	ds_read_b128 v[130:133], v128 offset:96
	s_waitcnt lgkmcnt(0)
	v_mfma_f32_32x32x16_bf16 v[48:63], v[130:133], v[80:83], v[48:63]
	ds_read_b128 v[130:133], v128 offset:6752
	s_waitcnt lgkmcnt(0)
	v_mfma_f32_32x32x16_bf16 v[32:47], v[130:133], v[80:83], v[32:47]
	ds_read_b128 v[130:133], v128 offset:128
	s_waitcnt lgkmcnt(0)
	v_mfma_f32_32x32x16_bf16 v[48:63], v[130:133], v[92:95], v[48:63]
	ds_read_b128 v[130:133], v128 offset:6784
	s_waitcnt lgkmcnt(0)
	v_mfma_f32_32x32x16_bf16 v[32:47], v[130:133], v[92:95], v[32:47]
	ds_read_b128 v[130:133], v128 offset:160
	s_waitcnt lgkmcnt(0)
	v_mfma_f32_32x32x16_bf16 v[48:63], v[130:133], v[88:91], v[48:63]
	ds_read_b128 v[130:133], v128 offset:6816
	s_waitcnt lgkmcnt(0)
	v_mfma_f32_32x32x16_bf16 v[32:47], v[130:133], v[88:91], v[32:47]
	s_nop 11
	v_max_f32_e32 v128, v32, v32
	v_max_f32_e32 v130, v48, v48
	v_max_f32_e32 v128, v130, v128
	v_max_f32_e32 v130, v33, v33
	v_max_f32_e32 v131, v49, v49
	v_max_f32_e32 v130, v131, v130
	v_max3_f32 v128, v108, v128, v130
	v_max_f32_e32 v130, v34, v34
	v_max_f32_e32 v131, v50, v50
	v_max_f32_e32 v130, v131, v130
	v_max_f32_e32 v131, v35, v35
	v_max_f32_e32 v132, v51, v51
	v_max_f32_e32 v131, v132, v131
	v_max3_f32 v128, v128, v130, v131
	v_max_f32_e32 v130, v36, v36
	v_max_f32_e32 v131, v52, v52
	v_max_f32_e32 v130, v131, v130
	v_max_f32_e32 v131, v37, v37
	v_max_f32_e32 v132, v53, v53
	v_max_f32_e32 v131, v132, v131
	v_max3_f32 v128, v128, v130, v131
	v_max_f32_e32 v130, v38, v38
	v_max_f32_e32 v131, v54, v54
	v_max_f32_e32 v130, v131, v130
	v_max_f32_e32 v131, v39, v39
	v_max_f32_e32 v132, v55, v55
	v_max_f32_e32 v131, v132, v131
	v_max3_f32 v128, v128, v130, v131
	v_max_f32_e32 v130, v40, v40
	v_max_f32_e32 v131, v56, v56
	v_max_f32_e32 v130, v131, v130
	v_max_f32_e32 v131, v41, v41
	v_max_f32_e32 v132, v57, v57
	v_max_f32_e32 v131, v132, v131
	v_max3_f32 v128, v128, v130, v131
	v_max_f32_e32 v130, v42, v42
	v_max_f32_e32 v131, v58, v58
	v_max_f32_e32 v130, v131, v130
	v_max_f32_e32 v131, v43, v43
	v_max_f32_e32 v132, v59, v59
	v_max_f32_e32 v131, v132, v131
	v_max3_f32 v128, v128, v130, v131
	v_max_f32_e32 v130, v44, v44
	v_max_f32_e32 v131, v60, v60
	v_max_f32_e32 v130, v131, v130
	v_max_f32_e32 v131, v45, v45
	v_max_f32_e32 v132, v61, v61
	v_max_f32_e32 v131, v132, v131
	v_max3_f32 v128, v128, v130, v131
	v_max_f32_e32 v130, v46, v46
	v_max_f32_e32 v131, v62, v62
	v_max_f32_e32 v130, v131, v130
	v_max_f32_e32 v131, v47, v47
	v_max_f32_e32 v132, v63, v63
	v_max_f32_e32 v131, v132, v131
	v_max3_f32 v128, v128, v130, v131
	ds_bpermute_b32 v130, v171, v128
	v_add3_u32 v140, s0, v175, v122
	s_waitcnt lgkmcnt(0)
	v_max_f32_e32 v130, v130, v130
	v_max_f32_e32 v128, v128, v130
	v_pk_add_f32 v[48:49], v[48:49], v[128:129] op_sel_hi:[1,0] neg_lo:[0,1] neg_hi:[0,1]
	v_pk_add_f32 v[32:33], v[32:33], v[128:129] op_sel_hi:[1,0] neg_lo:[0,1] neg_hi:[0,1]
	v_exp_f32_e32 v130, v48
	v_exp_f32_e32 v131, v49
	v_exp_f32_e32 v32, v32
	v_exp_f32_e32 v33, v33
	v_pk_add_f32 v[48:49], v[50:51], v[128:129] op_sel_hi:[1,0] neg_lo:[0,1] neg_hi:[0,1]
	v_pk_add_f32 v[34:35], v[34:35], v[128:129] op_sel_hi:[1,0] neg_lo:[0,1] neg_hi:[0,1]
	v_exp_f32_e32 v132, v48
	v_exp_f32_e32 v133, v49
	v_exp_f32_e32 v48, v34
	v_exp_f32_e32 v49, v35
	v_pk_add_f32 v[50:51], v[52:53], v[128:129] op_sel_hi:[1,0] neg_lo:[0,1] neg_hi:[0,1]
	v_pk_add_f32 v[36:37], v[36:37], v[128:129] op_sel_hi:[1,0] neg_lo:[0,1] neg_hi:[0,1]
	v_exp_f32_e32 v136, v50
	v_exp_f32_e32 v137, v51
	v_exp_f32_e32 v50, v36
	v_exp_f32_e32 v51, v37
	v_pk_add_f32 v[34:35], v[32:33], v[130:131]
	v_pk_add_f32 v[134:135], v[48:49], v[132:133]
	v_pk_add_f32 v[34:35], v[34:35], 0 op_sel_hi:[1,0]
	v_pk_add_f32 v[36:37], v[54:55], v[128:129] op_sel_hi:[1,0] neg_lo:[0,1] neg_hi:[0,1]
	v_pk_add_f32 v[38:39], v[38:39], v[128:129] op_sel_hi:[1,0] neg_lo:[0,1] neg_hi:[0,1]
	v_exp_f32_e32 v54, v36
	v_exp_f32_e32 v55, v37
	v_pk_add_f32 v[34:35], v[134:135], v[34:35]
	v_pk_add_f32 v[36:37], v[50:51], v[136:137]
	v_exp_f32_e32 v52, v38
	v_exp_f32_e32 v53, v39
	v_pk_add_f32 v[38:39], v[36:37], v[34:35]
	v_pk_add_f32 v[34:35], v[56:57], v[128:129] op_sel_hi:[1,0] neg_lo:[0,1] neg_hi:[0,1]
	v_pk_add_f32 v[36:37], v[40:41], v[128:129] op_sel_hi:[1,0] neg_lo:[0,1] neg_hi:[0,1]
	v_exp_f32_e32 v138, v34
	v_exp_f32_e32 v139, v35
	v_exp_f32_e32 v34, v36
	v_exp_f32_e32 v35, v37
	v_pk_add_f32 v[134:135], v[52:53], v[54:55]
	v_pk_add_f32 v[36:37], v[58:59], v[128:129] op_sel_hi:[1,0] neg_lo:[0,1] neg_hi:[0,1]
	v_pk_add_f32 v[40:41], v[42:43], v[128:129] op_sel_hi:[1,0] neg_lo:[0,1] neg_hi:[0,1]
	v_exp_f32_e32 v58, v36
	v_exp_f32_e32 v59, v37
	v_exp_f32_e32 v36, v40
	v_exp_f32_e32 v37, v41
	v_pk_add_f32 v[38:39], v[134:135], v[38:39]
	v_pk_add_f32 v[40:41], v[34:35], v[138:139]
	v_pk_add_f32 v[44:45], v[44:45], v[128:129] op_sel_hi:[1,0] neg_lo:[0,1] neg_hi:[0,1]
	v_pk_add_f32 v[40:41], v[40:41], v[38:39]
	v_pk_add_f32 v[38:39], v[60:61], v[128:129] op_sel_hi:[1,0] neg_lo:[0,1] neg_hi:[0,1]
	v_pk_add_f32 v[46:47], v[46:47], v[128:129] op_sel_hi:[1,0] neg_lo:[0,1] neg_hi:[0,1]
	v_exp_f32_e32 v60, v38
	v_exp_f32_e32 v61, v39
	v_exp_f32_e32 v38, v44
	v_exp_f32_e32 v39, v45
	v_pk_add_f32 v[44:45], v[62:63], v[128:129] op_sel_hi:[1,0] neg_lo:[0,1] neg_hi:[0,1]
	v_exp_f32_e32 v134, v46
	v_exp_f32_e32 v62, v44
	v_exp_f32_e32 v63, v45
	v_exp_f32_e32 v135, v47
	v_pk_add_f32 v[42:43], v[36:37], v[58:59]
	v_sub_f32_e32 v108, v108, v128
	v_pk_add_f32 v[40:41], v[42:43], v[40:41]
	v_pk_add_f32 v[42:43], v[38:39], v[60:61]
	v_exp_f32_e32 v44, v108
	v_pk_add_f32 v[40:41], v[42:43], v[40:41]
	v_pk_add_f32 v[42:43], v[134:135], v[62:63]
	v_pk_mul_f32 v[30:31], v[30:31], v[44:45] op_sel_hi:[1,0]
	v_pk_add_f32 v[40:41], v[42:43], v[40:41]
	v_pk_mul_f32 v[28:29], v[28:29], v[44:45] op_sel_hi:[1,0]
	v_add_f32_e32 v40, v40, v41
	ds_bpermute_b32 v41, v171, v40
	v_pk_mul_f32 v[26:27], v[26:27], v[44:45] op_sel_hi:[1,0]
	v_pk_mul_f32 v[24:25], v[24:25], v[44:45] op_sel_hi:[1,0]
	v_pk_mul_f32 v[22:23], v[22:23], v[44:45] op_sel_hi:[1,0]
	v_pk_mul_f32 v[20:21], v[20:21], v[44:45] op_sel_hi:[1,0]
	s_waitcnt lgkmcnt(0)
	v_add_f32_e32 v108, v40, v41
	v_pk_mul_f32 v[18:19], v[18:19], v[44:45] op_sel_hi:[1,0]
	v_pk_mul_f32 v[16:17], v[16:17], v[44:45] op_sel_hi:[1,0]
	v_pk_mul_f32 v[14:15], v[14:15], v[44:45] op_sel_hi:[1,0]
	v_pk_mul_f32 v[12:13], v[12:13], v[44:45] op_sel_hi:[1,0]
	v_pk_mul_f32 v[10:11], v[10:11], v[44:45] op_sel_hi:[1,0]
	v_pk_mul_f32 v[8:9], v[8:9], v[44:45] op_sel_hi:[1,0]
	v_pk_mul_f32 v[6:7], v[6:7], v[44:45] op_sel_hi:[1,0]
	v_pk_mul_f32 v[4:5], v[4:5], v[44:45] op_sel_hi:[1,0]
	v_pk_mul_f32 v[2:3], v[2:3], v[44:45] op_sel_hi:[1,0]
	v_pk_mul_f32 v[0:1], v[0:1], v[44:45] op_sel_hi:[1,0]
	v_fmac_f32_e32 v108, v177, v44
	v_cvt_pk_bf16_f32 v40, v130, v131
	v_add_u32_e32 v130, 0x3000, v140
	v_cvt_pk_bf16_f32 v43, v54, v55
	ds_read2_b64 v[44:47], v130 offset0:128 offset1:130
	ds_read2_b64 v[54:57], v130 offset0:132 offset1:134
	v_cvt_pk_bf16_f32 v41, v132, v133
	v_cvt_pk_bf16_f32 v42, v136, v137
	v_add_u32_e32 v131, 0x4000, v140
	s_waitcnt lgkmcnt(1)
	v_mfma_f32_32x32x16_bf16 v[16:31], v[44:47], v[40:43], v[16:31]
	ds_read2_b64 v[44:47], v131 offset0:160 offset1:162
	s_waitcnt lgkmcnt(0)
	v_mfma_f32_32x32x16_bf16 v[0:15], v[44:47], v[40:43], v[0:15]
	ds_read2_b64 v[44:47], v131 offset0:164 offset1:166
	v_cvt_pk_bf16_f32 v40, v138, v139
	v_cvt_pk_bf16_f32 v41, v58, v59
	v_cvt_pk_bf16_f32 v42, v60, v61
	v_cvt_pk_bf16_f32 v43, v62, v63
	s_nop 1
	v_mfma_f32_32x32x16_bf16 v[16:31], v[54:57], v[40:43], v[16:31]
	s_waitcnt lgkmcnt(0)
	v_mfma_f32_32x32x16_bf16 v[0:15], v[44:47], v[40:43], v[0:15]
	v_cvt_pk_bf16_f32 v41, v48, v49
	v_cvt_pk_bf16_f32 v42, v50, v51
	ds_read2_b64 v[44:47], v130 offset0:136 offset1:138
	ds_read2_b64 v[48:51], v130 offset0:140 offset1:142
	v_cvt_pk_bf16_f32 v40, v32, v33
	v_cvt_pk_bf16_f32 v43, v52, v53
	v_cvt_pk_bf16_f32 v32, v34, v35
	v_cvt_pk_bf16_f32 v33, v36, v37
	s_waitcnt lgkmcnt(1)
	v_mfma_f32_32x32x16_bf16 v[16:31], v[44:47], v[40:43], v[16:31]
	ds_read2_b64 v[44:47], v131 offset0:168 offset1:170
	v_cvt_pk_bf16_f32 v34, v38, v39
	ds_read2_b64 v[36:39], v131 offset0:172 offset1:174
	v_cvt_pk_bf16_f32 v35, v134, v135
	s_waitcnt lgkmcnt(1)
	v_mfma_f32_32x32x16_bf16 v[0:15], v[44:47], v[40:43], v[0:15]
	v_mfma_f32_32x32x16_bf16 v[16:31], v[48:51], v[32:35], v[16:31]
	s_waitcnt lgkmcnt(0)
	v_mfma_f32_32x32x16_bf16 v[0:15], v[36:39], v[32:35], v[0:15]
	v_add3_u32 v32, s6, v123, v125
	s_waitcnt vmcnt(4)
	ds_write_b128 v32, v[64:67]
	v_add3_u32 v32, s6, v129, v166
	s_waitcnt vmcnt(3)
	ds_write_b128 v32, v[76:79]
	v_add3_u32 v32, s6, v167, v168
	s_waitcnt vmcnt(2)
	ds_write_b128 v32, v[96:99]
	v_add_u32_e32 v32, s6, v169
	v_add3_u32 v32, v32, v124, s63
	s_waitcnt vmcnt(1)
	ds_write2_b64 v32, v[100:101], v[102:103] offset1:1
	v_add_u32_e32 v32, s6, v170
	v_add3_u32 v32, v32, v124, s63
	s_waitcnt vmcnt(0)
	ds_write2_b64 v32, v[104:105], v[106:107] offset1:1
	s_waitcnt lgkmcnt(0)
	s_barrier
	ds_read_b128 v[32:35], v173
	ds_read_b128 v[64:67], v173 offset:32
	s_waitcnt lgkmcnt(1)
	v_mfma_f32_32x32x16_bf16 v[48:63], v[32:35], v[68:71], 0
	ds_read_b128 v[32:35], v173 offset:6656
	s_waitcnt lgkmcnt(1)
	v_mfma_f32_32x32x16_bf16 v[48:63], v[64:67], v[72:75], v[48:63]
	ds_read_b128 v[64:67], v173 offset:6688
	s_waitcnt lgkmcnt(1)
	v_mfma_f32_32x32x16_bf16 v[32:47], v[32:35], v[68:71], 0
	s_waitcnt lgkmcnt(0)
	v_mfma_f32_32x32x16_bf16 v[32:47], v[64:67], v[72:75], v[32:47]
	ds_read_b128 v[64:67], v173 offset:64
	s_waitcnt lgkmcnt(0)
	v_mfma_f32_32x32x16_bf16 v[48:63], v[64:67], v[84:87], v[48:63]
	ds_read_b128 v[64:67], v173 offset:6720
	s_waitcnt lgkmcnt(0)
	v_mfma_f32_32x32x16_bf16 v[32:47], v[64:67], v[84:87], v[32:47]
	ds_read_b128 v[64:67], v173 offset:96
	s_waitcnt lgkmcnt(0)
	v_mfma_f32_32x32x16_bf16 v[48:63], v[64:67], v[80:83], v[48:63]
	ds_read_b128 v[64:67], v173 offset:6752
	s_waitcnt lgkmcnt(0)
	v_mfma_f32_32x32x16_bf16 v[32:47], v[64:67], v[80:83], v[32:47]
	ds_read_b128 v[64:67], v173 offset:128
	s_waitcnt lgkmcnt(0)
	v_mfma_f32_32x32x16_bf16 v[48:63], v[64:67], v[92:95], v[48:63]
	ds_read_b128 v[64:67], v173 offset:6784
	s_waitcnt lgkmcnt(0)
	v_mfma_f32_32x32x16_bf16 v[32:47], v[64:67], v[92:95], v[32:47]
	ds_read_b128 v[64:67], v173 offset:160
	s_waitcnt lgkmcnt(0)
	v_mfma_f32_32x32x16_bf16 v[48:63], v[64:67], v[88:91], v[48:63]
	ds_read_b128 v[64:67], v173 offset:6816
	s_waitcnt lgkmcnt(0)
	v_mfma_f32_32x32x16_bf16 v[32:47], v[64:67], v[88:91], v[32:47]
	s_nop 11
	v_max_f32_e32 v64, v32, v32
	v_max_f32_e32 v65, v48, v48
	v_max_f32_e32 v64, v65, v64
	v_max_f32_e32 v65, v33, v33
	v_max_f32_e32 v66, v49, v49
	v_max_f32_e32 v65, v66, v65
	v_max3_f32 v64, v128, v64, v65
	v_max_f32_e32 v65, v34, v34
	v_max_f32_e32 v66, v50, v50
	v_max_f32_e32 v65, v66, v65
	v_max_f32_e32 v66, v35, v35
	v_max_f32_e32 v67, v51, v51
	v_max_f32_e32 v66, v67, v66
	v_max3_f32 v64, v64, v65, v66
	v_max_f32_e32 v65, v36, v36
	v_max_f32_e32 v66, v52, v52
	v_max_f32_e32 v65, v66, v65
	v_max_f32_e32 v66, v37, v37
	v_max_f32_e32 v67, v53, v53
	v_max_f32_e32 v66, v67, v66
	v_max3_f32 v64, v64, v65, v66
	v_max_f32_e32 v65, v38, v38
	v_max_f32_e32 v66, v54, v54
	v_max_f32_e32 v65, v66, v65
	v_max_f32_e32 v66, v39, v39
	v_max_f32_e32 v67, v55, v55
	v_max_f32_e32 v66, v67, v66
	v_max3_f32 v64, v64, v65, v66
	v_max_f32_e32 v65, v40, v40
	v_max_f32_e32 v66, v56, v56
	v_max_f32_e32 v65, v66, v65
	v_max_f32_e32 v66, v41, v41
	v_max_f32_e32 v67, v57, v57
	v_max_f32_e32 v66, v67, v66
	v_max3_f32 v64, v64, v65, v66
	v_max_f32_e32 v65, v42, v42
	v_max_f32_e32 v66, v58, v58
	v_max_f32_e32 v65, v66, v65
	v_max_f32_e32 v66, v43, v43
	v_max_f32_e32 v67, v59, v59
	v_max_f32_e32 v66, v67, v66
	v_max3_f32 v64, v64, v65, v66
	v_max_f32_e32 v65, v44, v44
	v_max_f32_e32 v66, v60, v60
	v_max_f32_e32 v65, v66, v65
	v_max_f32_e32 v66, v45, v45
	v_max_f32_e32 v67, v61, v61
	v_max_f32_e32 v66, v67, v66
	v_max3_f32 v64, v64, v65, v66
	v_max_f32_e32 v65, v46, v46
	v_max_f32_e32 v66, v62, v62
	v_max_f32_e32 v65, v66, v65
	v_max_f32_e32 v66, v47, v47
	v_max_f32_e32 v67, v63, v63
	v_max_f32_e32 v66, v67, v66
	v_max3_f32 v64, v64, v65, v66
	ds_bpermute_b32 v65, v171, v64
	s_waitcnt lgkmcnt(0)
	v_max_f32_e32 v65, v65, v65
	v_max_f32_e32 v64, v64, v65
	v_pk_add_f32 v[48:49], v[48:49], v[64:65] op_sel_hi:[1,0] neg_lo:[0,1] neg_hi:[0,1]
	v_pk_add_f32 v[32:33], v[32:33], v[64:65] op_sel_hi:[1,0] neg_lo:[0,1] neg_hi:[0,1]
	v_exp_f32_e32 v66, v48
	v_exp_f32_e32 v67, v49
	v_exp_f32_e32 v32, v32
	v_exp_f32_e32 v33, v33
	v_pk_add_f32 v[48:49], v[50:51], v[64:65] op_sel_hi:[1,0] neg_lo:[0,1] neg_hi:[0,1]
	v_pk_add_f32 v[34:35], v[34:35], v[64:65] op_sel_hi:[1,0] neg_lo:[0,1] neg_hi:[0,1]
	v_sub_f32_e32 v65, v128, v64
	v_exp_f32_e32 v68, v48
	v_exp_f32_e32 v69, v49
	v_exp_f32_e32 v48, v34
	v_exp_f32_e32 v49, v35
	v_pk_add_f32 v[50:51], v[52:53], v[64:65] op_sel_hi:[1,0] neg_lo:[0,1] neg_hi:[0,1]
	v_pk_add_f32 v[36:37], v[36:37], v[64:65] op_sel_hi:[1,0] neg_lo:[0,1] neg_hi:[0,1]
	v_exp_f32_e32 v52, v50
	v_exp_f32_e32 v53, v51
	v_exp_f32_e32 v50, v36
	v_exp_f32_e32 v51, v37
	v_pk_add_f32 v[34:35], v[32:33], v[66:67]
	v_pk_add_f32 v[36:37], v[54:55], v[64:65] op_sel_hi:[1,0] neg_lo:[0,1] neg_hi:[0,1]
	v_pk_add_f32 v[38:39], v[38:39], v[64:65] op_sel_hi:[1,0] neg_lo:[0,1] neg_hi:[0,1]
	v_pk_add_f32 v[34:35], v[34:35], 0 op_sel_hi:[1,0]
	v_pk_add_f32 v[70:71], v[48:49], v[68:69]
	v_exp_f32_e32 v54, v36
	v_exp_f32_e32 v55, v37
	v_exp_f32_e32 v72, v38
	v_exp_f32_e32 v73, v39
	v_pk_add_f32 v[34:35], v[70:71], v[34:35]
	v_pk_add_f32 v[36:37], v[50:51], v[52:53]
	v_pk_add_f32 v[44:45], v[44:45], v[64:65] op_sel_hi:[1,0] neg_lo:[0,1] neg_hi:[0,1]
	v_pk_add_f32 v[38:39], v[36:37], v[34:35]
	v_pk_add_f32 v[34:35], v[56:57], v[64:65] op_sel_hi:[1,0] neg_lo:[0,1] neg_hi:[0,1]
	v_pk_add_f32 v[36:37], v[40:41], v[64:65] op_sel_hi:[1,0] neg_lo:[0,1] neg_hi:[0,1]
	v_exp_f32_e32 v56, v34
	v_exp_f32_e32 v57, v35
	v_exp_f32_e32 v34, v36
	v_exp_f32_e32 v35, v37
	v_pk_add_f32 v[36:37], v[58:59], v[64:65] op_sel_hi:[1,0] neg_lo:[0,1] neg_hi:[0,1]
	v_pk_add_f32 v[40:41], v[42:43], v[64:65] op_sel_hi:[1,0] neg_lo:[0,1] neg_hi:[0,1]
	v_pk_add_f32 v[70:71], v[72:73], v[54:55]
	v_exp_f32_e32 v58, v36
	v_exp_f32_e32 v59, v37
	v_exp_f32_e32 v36, v40
	v_exp_f32_e32 v37, v41
	v_pk_add_f32 v[42:43], v[60:61], v[64:65] op_sel_hi:[1,0] neg_lo:[0,1] neg_hi:[0,1]
	v_pk_add_f32 v[38:39], v[70:71], v[38:39]
	v_exp_f32_e32 v60, v42
	v_exp_f32_e32 v61, v43
	v_exp_f32_e32 v70, v44
	v_exp_f32_e32 v71, v45
	v_pk_add_f32 v[42:43], v[62:63], v[64:65] op_sel_hi:[1,0] neg_lo:[0,1] neg_hi:[0,1]
	v_pk_add_f32 v[44:45], v[46:47], v[64:65] op_sel_hi:[1,0] neg_lo:[0,1] neg_hi:[0,1]
	v_exp_f32_e32 v46, v42
	v_exp_f32_e32 v47, v43
	v_exp_f32_e32 v62, v44
	v_exp_f32_e32 v63, v45
	v_pk_add_f32 v[40:41], v[34:35], v[56:57]
	v_exp_f32_e32 v64, v65
	v_pk_add_f32 v[38:39], v[40:41], v[38:39]
	v_pk_add_f32 v[40:41], v[36:37], v[58:59]
	s_nop 0
	v_pk_add_f32 v[38:39], v[40:41], v[38:39]
	v_pk_add_f32 v[40:41], v[70:71], v[60:61]
	s_nop 0
	v_pk_add_f32 v[38:39], v[40:41], v[38:39]
	v_pk_add_f32 v[40:41], v[62:63], v[46:47]
	s_nop 0
	v_pk_add_f32 v[38:39], v[40:41], v[38:39]
	s_nop 0
	v_add_f32_e32 v65, v38, v39
	ds_bpermute_b32 v74, v171, v65
	v_pk_mul_f32 v[30:31], v[30:31], v[64:65] op_sel_hi:[1,0]
	v_pk_mul_f32 v[28:29], v[28:29], v[64:65] op_sel_hi:[1,0]
	v_pk_mul_f32 v[26:27], v[26:27], v[64:65] op_sel_hi:[1,0]
	v_pk_mul_f32 v[24:25], v[24:25], v[64:65] op_sel_hi:[1,0]
	v_pk_mul_f32 v[22:23], v[22:23], v[64:65] op_sel_hi:[1,0]
	v_pk_mul_f32 v[20:21], v[20:21], v[64:65] op_sel_hi:[1,0]
	v_pk_mul_f32 v[18:19], v[18:19], v[64:65] op_sel_hi:[1,0]
	v_pk_mul_f32 v[16:17], v[16:17], v[64:65] op_sel_hi:[1,0]
	v_pk_mul_f32 v[14:15], v[14:15], v[64:65] op_sel_hi:[1,0]
	v_pk_mul_f32 v[12:13], v[12:13], v[64:65] op_sel_hi:[1,0]
	v_pk_mul_f32 v[10:11], v[10:11], v[64:65] op_sel_hi:[1,0]
	v_pk_mul_f32 v[8:9], v[8:9], v[64:65] op_sel_hi:[1,0]
	v_pk_mul_f32 v[6:7], v[6:7], v[64:65] op_sel_hi:[1,0]
	v_pk_mul_f32 v[4:5], v[4:5], v[64:65] op_sel_hi:[1,0]
	v_pk_mul_f32 v[2:3], v[2:3], v[64:65] op_sel_hi:[1,0]
	v_pk_mul_f32 v[0:1], v[0:1], v[64:65] op_sel_hi:[1,0]
	v_cvt_pk_bf16_f32 v40, v52, v53
	v_cvt_pk_bf16_f32 v41, v54, v55
	ds_read2_b64 v[42:45], v174 offset0:128 offset1:130
	ds_read2_b64 v[52:55], v174 offset0:132 offset1:134
	v_cvt_pk_bf16_f32 v38, v66, v67
	v_cvt_pk_bf16_f32 v39, v68, v69
	s_waitcnt lgkmcnt(1)
	s_nop 0
	v_mfma_f32_32x32x16_bf16 v[16:31], v[42:45], v[38:41], v[16:31]
	ds_read2_b64 v[42:45], v172 offset0:160 offset1:162
	s_waitcnt lgkmcnt(0)
	v_mfma_f32_32x32x16_bf16 v[0:15], v[42:45], v[38:41], v[0:15]
	ds_read2_b64 v[42:45], v172 offset0:164 offset1:166
	v_cvt_pk_bf16_f32 v38, v56, v57
	v_cvt_pk_bf16_f32 v39, v58, v59
	v_cvt_pk_bf16_f32 v40, v60, v61
	v_cvt_pk_bf16_f32 v41, v46, v47
	s_nop 1
	v_mfma_f32_32x32x16_bf16 v[16:31], v[52:55], v[38:41], v[16:31]
	s_waitcnt lgkmcnt(0)
	v_mfma_f32_32x32x16_bf16 v[0:15], v[42:45], v[38:41], v[0:15]
	v_cvt_pk_bf16_f32 v39, v48, v49
	ds_read2_b64 v[42:45], v174 offset0:136 offset1:138
	ds_read2_b64 v[46:49], v174 offset0:140 offset1:142
	v_cvt_pk_bf16_f32 v38, v32, v33
	v_cvt_pk_bf16_f32 v40, v50, v51
	v_cvt_pk_bf16_f32 v41, v72, v73
	v_cvt_pk_bf16_f32 v33, v36, v37
	v_cvt_pk_bf16_f32 v32, v34, v35
	s_waitcnt lgkmcnt(1)
	v_mfma_f32_32x32x16_bf16 v[16:31], v[42:45], v[38:41], v[16:31]
	ds_read2_b64 v[42:45], v172 offset0:168 offset1:170
	v_cvt_pk_bf16_f32 v34, v70, v71
	v_cvt_pk_bf16_f32 v35, v62, v63
	s_waitcnt lgkmcnt(0)
	v_mfma_f32_32x32x16_bf16 v[0:15], v[42:45], v[38:41], v[0:15]
	ds_read2_b64 v[36:39], v172 offset0:172 offset1:174
	v_mfma_f32_32x32x16_bf16 v[16:31], v[46:49], v[32:35], v[16:31]
	s_waitcnt lgkmcnt(0)
	v_mfma_f32_32x32x16_bf16 v[0:15], v[36:39], v[32:35], v[0:15]
	v_add_f32_e32 v32, v65, v74
	v_fmac_f32_e32 v32, v108, v64
	v_div_scale_f32 v33, s[0:1], v32, v32, 1.0
	v_rcp_f32_e32 v34, v33
	v_mov_b32_e32 v123, v109
	s_barrier
	v_fma_f32 v35, -v33, v34, 1.0
	v_fmac_f32_e32 v34, v35, v34
	v_div_scale_f32 v35, vcc, 1.0, v32, 1.0
	v_mul_f32_e32 v36, v35, v34
	v_fma_f32 v37, -v33, v36, v35
	v_fmac_f32_e32 v36, v37, v34
	v_fma_f32 v33, -v33, v36, v35
	v_div_fmas_f32 v33, v33, v34, v36
	v_div_fixup_f32 v32, v33, v32, 1.0
	v_pk_mul_f32 v[0:1], v[32:33], v[0:1] op_sel_hi:[0,1]
	v_pk_mul_f32 v[2:3], v[32:33], v[2:3] op_sel_hi:[0,1]
	v_lshl_add_u64 v[34:35], v[126:127], 0, v[122:123]
	v_cvt_pk_bf16_f32 v0, v0, v1
	v_cvt_pk_bf16_f32 v1, v2, v3
	global_store_dwordx2 v[34:35], v[0:1], off offset:64
	v_pk_mul_f32 v[0:1], v[32:33], v[20:21] op_sel_hi:[0,1]
	v_pk_mul_f32 v[2:3], v[32:33], v[22:23] op_sel_hi:[0,1]
	v_cvt_pk_bf16_f32 v0, v0, v1
	v_cvt_pk_bf16_f32 v1, v2, v3
	global_store_dwordx2 v[34:35], v[0:1], off offset:16
	v_pk_mul_f32 v[0:1], v[32:33], v[4:5] op_sel_hi:[0,1]
	v_pk_mul_f32 v[2:3], v[32:33], v[6:7] op_sel_hi:[0,1]
	v_cvt_pk_bf16_f32 v0, v0, v1
	v_cvt_pk_bf16_f32 v1, v2, v3
	global_store_dwordx2 v[34:35], v[0:1], off offset:80
	v_pk_mul_f32 v[0:1], v[32:33], v[24:25] op_sel_hi:[0,1]
	v_pk_mul_f32 v[2:3], v[32:33], v[26:27] op_sel_hi:[0,1]
	v_cvt_pk_bf16_f32 v0, v0, v1
	v_cvt_pk_bf16_f32 v1, v2, v3
	global_store_dwordx2 v[34:35], v[0:1], off offset:32
	v_pk_mul_f32 v[0:1], v[32:33], v[8:9] op_sel_hi:[0,1]
	v_pk_mul_f32 v[2:3], v[32:33], v[10:11] op_sel_hi:[0,1]
	v_cvt_pk_bf16_f32 v0, v0, v1
	v_cvt_pk_bf16_f32 v1, v2, v3
	global_store_dwordx2 v[34:35], v[0:1], off offset:96
	v_pk_mul_f32 v[0:1], v[32:33], v[28:29] op_sel_hi:[0,1]
	v_pk_mul_f32 v[2:3], v[32:33], v[30:31] op_sel_hi:[0,1]
	v_cvt_pk_bf16_f32 v0, v0, v1
	v_cvt_pk_bf16_f32 v1, v2, v3
	v_pk_mul_f32 v[16:17], v[32:33], v[16:17] op_sel_hi:[0,1]
	v_pk_mul_f32 v[18:19], v[32:33], v[18:19] op_sel_hi:[0,1]
	global_store_dwordx2 v[34:35], v[0:1], off offset:48
	v_pk_mul_f32 v[0:1], v[32:33], v[12:13] op_sel_hi:[0,1]
	v_pk_mul_f32 v[2:3], v[32:33], v[14:15] op_sel_hi:[0,1]
	v_cvt_pk_bf16_f32 v16, v16, v17
	v_cvt_pk_bf16_f32 v17, v18, v19
	v_cvt_pk_bf16_f32 v0, v0, v1
	v_cvt_pk_bf16_f32 v1, v2, v3
	global_store_dwordx2 v[34:35], v[16:17], off
	global_store_dwordx2 v[34:35], v[0:1], off offset:112
	s_cbranch_execnz .LBB0_643
	s_branch .LBB0_712

	.amdhsa_kernel _Z11mega_kernel6Params
		.amdhsa_group_segment_fixed_size 66048
		.amdhsa_private_segment_fixed_size 0
		.amdhsa_kernarg_size 512
		.amdhsa_user_sgpr_count 2
		.amdhsa_user_sgpr_dispatch_ptr 0
		.amdhsa_user_sgpr_queue_ptr 0
		.amdhsa_user_sgpr_kernarg_segment_ptr 1
		.amdhsa_user_sgpr_dispatch_id 0
		.amdhsa_user_sgpr_kernarg_preload_length 0
		.amdhsa_user_sgpr_kernarg_preload_offset 0
		.amdhsa_user_sgpr_private_segment_size 0
		.amdhsa_uses_dynamic_stack 0
		.amdhsa_enable_private_segment 0
		.amdhsa_system_sgpr_workgroup_id_x 1
		.amdhsa_system_sgpr_workgroup_id_y 0
		.amdhsa_system_sgpr_workgroup_id_z 0
		.amdhsa_system_sgpr_workgroup_info 0
		.amdhsa_system_vgpr_workitem_id 2
		.amdhsa_next_free_vgpr 256
		.amdhsa_next_free_sgpr 100
		.amdhsa_accum_offset 256
		.amdhsa_reserve_vcc 1
		.amdhsa_float_round_mode_32 0
		.amdhsa_float_round_mode_16_64 0
		.amdhsa_float_denorm_mode_32 3
		.amdhsa_float_denorm_mode_16_64 3
		.amdhsa_dx10_clamp 1
		.amdhsa_ieee_mode 1
		.amdhsa_fp16_overflow 0
		.amdhsa_tg_split 0
		.amdhsa_exception_fp_ieee_invalid_op 0
		.amdhsa_exception_fp_denorm_src 0
		.amdhsa_exception_fp_ieee_div_zero 0
		.amdhsa_exception_fp_ieee_overflow 0
		.amdhsa_exception_fp_ieee_underflow 0
		.amdhsa_exception_fp_ieee_inexact 0
		.amdhsa_exception_int_div_zero 0
	.end_amdhsa_kernel

amdhsa.kernels:
  - .agpr_count:     0
    .args:
      - .offset:         0
        .size:           256
        .value_kind:     by_value
      - .offset:         256
        .size:           4
        .value_kind:     hidden_block_count_x
      - .offset:         260
        .size:           4
        .value_kind:     hidden_block_count_y
      - .offset:         264
        .size:           4
        .value_kind:     hidden_block_count_z
      - .offset:         268
        .size:           2
        .value_kind:     hidden_group_size_x
      - .offset:         270
        .size:           2
        .value_kind:     hidden_group_size_y
      - .offset:         272
        .size:           2
        .value_kind:     hidden_group_size_z
      - .offset:         274
        .size:           2
        .value_kind:     hidden_remainder_x
      - .offset:         276
        .size:           2
        .value_kind:     hidden_remainder_y
      - .offset:         278
        .size:           2
        .value_kind:     hidden_remainder_z
      - .offset:         296
        .size:           8
        .value_kind:     hidden_global_offset_x
      - .offset:         304
        .size:           8
        .value_kind:     hidden_global_offset_y
      - .offset:         312
        .size:           8
        .value_kind:     hidden_global_offset_z
      - .offset:         320
        .size:           2
        .value_kind:     hidden_grid_dims
      - .offset:         344
        .size:           8
        .value_kind:     hidden_multigrid_sync_arg
    .group_segment_fixed_size: 66048
    .kernarg_segment_align: 8
    .kernarg_segment_size: 512
    .language:       OpenCL C
    .language_version:
      - 2
      - 0
    .max_flat_workgroup_size: 256
    .name:           _Z11mega_kernel6Params
    .private_segment_fixed_size: 0
    .sgpr_count:     106
    .sgpr_spill_count: 134
    .symbol:         _Z11mega_kernel6Params.kd
    .uniform_work_group_size: 1
    .uses_dynamic_stack: false
    .vgpr_count:     256
    .vgpr_spill_count: 0
    .wavefront_size: 64
